# key conversion as one unconditional 3-op pass plus a separate causal pass on the diagonal tile only (smaller code than v81)
# speedup vs baseline: 1.0045x; 1.0001x over previous
; #define MFMA32(a, b, c) __builtin_amdgcn_mfma_f32_32x32x16_bf16((a), (b), (c), 0, 0, 0)
; DI void a1_task(unsigned char* shm, const bf16_t* prm, const bf16_t* prt, unsigned* mask, int b, int qt, const int tid) {
;     ...
;             for (int hh = 0; hh < 8; ++hh) {
;                 bf16x8 qa[4];
; #pragma unroll
;                 for (int ks = 0; ks < 4; ++ks) qa[ks] = *(const bf16x8*)(qb0 + hh * 128 + 32 * ks);
;                 const float wv = wqs[hh * 32 + r];
;                 asm volatile("s_waitcnt lgkmcnt(0)" ::: "memory");
;                 f32x16 acc;
; #pragma unroll
;                 for (int i = 0; i < 16; ++i) acc[i] = 0.f;
; #pragma unroll
;                 for (int ks = 0; ks < 4; ++ks) acc = MFMA32(kf[ks], qa[ks], acc);
; #pragma unroll
;                 for (int i = 0; i < 16; ++i) idx[i] = fmaf(wv, fmaxf(acc[i], 0.f), idx[i]);
;             }
; #pragma unroll
;             for (int i = 0; i < 16; ++i) {
;                 const int s = s0 + 16 * (i >> 3) + 8 * h + (i & 7);
;                 const unsigned u = __float_as_uint(idx[i] + 0.0f);
;                 const unsigned k = (u & 0x80000000u) ? ~u : (u | 0x80000000u);
;                 key[jt][i] = (s <= t0 + r) ? k : 0u;
;             }
.LBB0_389:
	v_add_u32_e32 v79, s1, v118
	ds_read_b128 v[2:5], v79
	ds_read_b128 v[66:69], v79 offset:32
	ds_read_b128 v[70:73], v79 offset:64
	ds_read_b128 v[74:77], v79 offset:96
	v_add_u32_e32 v80, s1, v135
	s_waitcnt lgkmcnt(3)
	v_mfma_f32_32x32x16_bf16 v[2:17], v[50:53], v[2:5], 0
	ds_read_b32 v78, v80
	s_waitcnt lgkmcnt(0)
	s_addk_i32 s1, 0x100
	s_cmpk_eq_i32 s1, 0x400
	s_waitcnt lgkmcnt(3)
	v_mfma_f32_32x32x16_bf16 v[2:17], v[54:57], v[66:69], v[2:17]
	s_waitcnt lgkmcnt(2)
	v_mfma_f32_32x32x16_bf16 v[2:17], v[58:61], v[70:73], v[2:17]
	s_waitcnt lgkmcnt(1)
	v_mfma_f32_32x32x16_bf16 v[2:17], v[62:65], v[74:77], v[2:17]
	s_nop 11
	v_max_f32_e32 v2, 0, v2
	v_max_f32_e32 v3, 0, v3
	s_waitcnt lgkmcnt(0)
	v_pk_fma_f32 v[48:49], v[78:79], v[2:3], v[48:49] op_sel_hi:[0,1,1]
	v_max_f32_e32 v2, 0, v4
	v_max_f32_e32 v3, 0, v5
	v_pk_fma_f32 v[46:47], v[78:79], v[2:3], v[46:47] op_sel_hi:[0,1,1]
	v_max_f32_e32 v2, 0, v6
	v_max_f32_e32 v3, 0, v7
	v_pk_fma_f32 v[44:45], v[78:79], v[2:3], v[44:45] op_sel_hi:[0,1,1]
	v_max_f32_e32 v2, 0, v8
	v_max_f32_e32 v3, 0, v9
	v_pk_fma_f32 v[42:43], v[78:79], v[2:3], v[42:43] op_sel_hi:[0,1,1]
	v_max_f32_e32 v2, 0, v10
	v_max_f32_e32 v3, 0, v11
	v_pk_fma_f32 v[40:41], v[78:79], v[2:3], v[40:41] op_sel_hi:[0,1,1]
	v_max_f32_e32 v2, 0, v12
	v_max_f32_e32 v3, 0, v13
	v_pk_fma_f32 v[38:39], v[78:79], v[2:3], v[38:39] op_sel_hi:[0,1,1]
	v_max_f32_e32 v2, 0, v14
	v_max_f32_e32 v3, 0, v15
	v_pk_fma_f32 v[36:37], v[78:79], v[2:3], v[36:37] op_sel_hi:[0,1,1]
	v_max_f32_e32 v2, 0, v16
	v_max_f32_e32 v3, 0, v17
	v_pk_fma_f32 v[34:35], v[78:79], v[2:3], v[34:35] op_sel_hi:[0,1,1]
	ds_read_b128 v[2:5], v79 offset:128
	ds_read_b128 v[66:69], v79 offset:160
	ds_read_b128 v[70:73], v79 offset:192
	ds_read_b128 v[74:77], v79 offset:224
	ds_read_b32 v78, v80 offset:128
	s_waitcnt lgkmcnt(4)
	v_mfma_f32_32x32x16_bf16 v[2:17], v[50:53], v[2:5], 0
	s_waitcnt lgkmcnt(0)
	s_waitcnt lgkmcnt(3)
	v_mfma_f32_32x32x16_bf16 v[2:17], v[54:57], v[66:69], v[2:17]
	s_waitcnt lgkmcnt(2)
	v_mfma_f32_32x32x16_bf16 v[2:17], v[58:61], v[70:73], v[2:17]
	s_waitcnt lgkmcnt(1)
	v_mfma_f32_32x32x16_bf16 v[2:17], v[62:65], v[74:77], v[2:17]
	s_nop 11
	v_max_f32_e32 v2, 0, v2
	v_max_f32_e32 v3, 0, v3
	s_waitcnt lgkmcnt(0)
	v_pk_fma_f32 v[48:49], v[78:79], v[2:3], v[48:49] op_sel_hi:[0,1,1]
	v_max_f32_e32 v2, 0, v4
	v_max_f32_e32 v3, 0, v5
	v_pk_fma_f32 v[46:47], v[78:79], v[2:3], v[46:47] op_sel_hi:[0,1,1]
	v_max_f32_e32 v2, 0, v6
	v_max_f32_e32 v3, 0, v7
	v_pk_fma_f32 v[44:45], v[78:79], v[2:3], v[44:45] op_sel_hi:[0,1,1]
	v_max_f32_e32 v2, 0, v8
	v_max_f32_e32 v3, 0, v9
	v_pk_fma_f32 v[42:43], v[78:79], v[2:3], v[42:43] op_sel_hi:[0,1,1]
	v_max_f32_e32 v2, 0, v10
	v_max_f32_e32 v3, 0, v11
	v_pk_fma_f32 v[40:41], v[78:79], v[2:3], v[40:41] op_sel_hi:[0,1,1]
	v_max_f32_e32 v2, 0, v12
	v_max_f32_e32 v3, 0, v13
	v_pk_fma_f32 v[38:39], v[78:79], v[2:3], v[38:39] op_sel_hi:[0,1,1]
	v_max_f32_e32 v2, 0, v14
	v_max_f32_e32 v3, 0, v15
	v_pk_fma_f32 v[36:37], v[78:79], v[2:3], v[36:37] op_sel_hi:[0,1,1]
	v_max_f32_e32 v2, 0, v16
	v_max_f32_e32 v3, 0, v17
	v_pk_fma_f32 v[34:35], v[78:79], v[2:3], v[34:35] op_sel_hi:[0,1,1]
	s_cbranch_scc0 .LBB0_389
	v_pk_add_f32 v[2:3], v[48:49], 0 op_sel_hi:[1,0]
	v_ashrrev_i32_e32 v4, 31, v2
	v_ashrrev_i32_e32 v5, 31, v3
	v_or_b32_e32 v4, 0x80000000, v4
	v_or_b32_e32 v5, 0x80000000, v5
	v_xor_b32_e32 v142, v2, v4
	v_xor_b32_e32 v141, v3, v5
	v_pk_add_f32 v[2:3], v[46:47], 0 op_sel_hi:[1,0]
	v_ashrrev_i32_e32 v4, 31, v2
	v_ashrrev_i32_e32 v5, 31, v3
	v_or_b32_e32 v4, 0x80000000, v4
	v_or_b32_e32 v5, 0x80000000, v5
	v_xor_b32_e32 v144, v2, v4
	v_xor_b32_e32 v143, v3, v5
	v_pk_add_f32 v[2:3], v[44:45], 0 op_sel_hi:[1,0]
	v_ashrrev_i32_e32 v4, 31, v2
	v_ashrrev_i32_e32 v5, 31, v3
	v_or_b32_e32 v4, 0x80000000, v4
	v_or_b32_e32 v5, 0x80000000, v5
	v_xor_b32_e32 v146, v2, v4
	v_xor_b32_e32 v145, v3, v5
	v_pk_add_f32 v[2:3], v[42:43], 0 op_sel_hi:[1,0]
	v_ashrrev_i32_e32 v4, 31, v2
	v_ashrrev_i32_e32 v5, 31, v3
	v_or_b32_e32 v4, 0x80000000, v4
	v_or_b32_e32 v5, 0x80000000, v5
	v_xor_b32_e32 v149, v2, v4
	v_xor_b32_e32 v147, v3, v5
	v_pk_add_f32 v[2:3], v[40:41], 0 op_sel_hi:[1,0]
	v_ashrrev_i32_e32 v4, 31, v2
	v_ashrrev_i32_e32 v5, 31, v3
	v_or_b32_e32 v4, 0x80000000, v4
	v_or_b32_e32 v5, 0x80000000, v5
	v_xor_b32_e32 v151, v2, v4
	v_xor_b32_e32 v150, v3, v5
	v_pk_add_f32 v[2:3], v[38:39], 0 op_sel_hi:[1,0]
	v_ashrrev_i32_e32 v4, 31, v2
	v_ashrrev_i32_e32 v5, 31, v3
	v_or_b32_e32 v4, 0x80000000, v4
	v_or_b32_e32 v5, 0x80000000, v5
	v_xor_b32_e32 v153, v2, v4
	v_xor_b32_e32 v152, v3, v5
	v_pk_add_f32 v[2:3], v[36:37], 0 op_sel_hi:[1,0]
	v_ashrrev_i32_e32 v4, 31, v2
	v_ashrrev_i32_e32 v5, 31, v3
	v_or_b32_e32 v4, 0x80000000, v4
	v_or_b32_e32 v5, 0x80000000, v5
	v_xor_b32_e32 v155, v2, v4
	v_xor_b32_e32 v154, v3, v5
	v_pk_add_f32 v[2:3], v[34:35], 0 op_sel_hi:[1,0]
	v_ashrrev_i32_e32 v4, 31, v2
	v_ashrrev_i32_e32 v5, 31, v3
	v_or_b32_e32 v4, 0x80000000, v4
	v_or_b32_e32 v5, 0x80000000, v5
	v_xor_b32_e32 v157, v2, v4
	v_xor_b32_e32 v156, v3, v5
	s_lshr_b32 s98, s0, 5
	s_cmp_lt_u32 s98, s2
	s_cbranch_scc1 .Lkc_done_389
	v_or_b32_e32 v8, s0, v98
	v_cmp_le_i32_e64 s[98:99], v8, v0
	s_nop 1
	v_cndmask_b32_e64 v142, 0, v142, s[98:99]
	v_or_b32_e32 v6, 1, v8
	v_cmp_le_i32_e64 s[98:99], v6, v0
	s_nop 1
	v_cndmask_b32_e64 v141, 0, v141, s[98:99]
	v_or_b32_e32 v6, 2, v8
	v_cmp_le_i32_e64 s[98:99], v6, v0
	s_nop 1
	v_cndmask_b32_e64 v144, 0, v144, s[98:99]
	v_or_b32_e32 v6, 3, v8
	v_cmp_le_i32_e64 s[98:99], v6, v0
	s_nop 1
	v_cndmask_b32_e64 v143, 0, v143, s[98:99]
	v_or_b32_e32 v6, 4, v8
	v_cmp_le_i32_e64 s[98:99], v6, v0
	s_nop 1
	v_cndmask_b32_e64 v146, 0, v146, s[98:99]
	v_or_b32_e32 v6, 5, v8
	v_cmp_le_i32_e64 s[98:99], v6, v0
	s_nop 1
	v_cndmask_b32_e64 v145, 0, v145, s[98:99]
	v_or_b32_e32 v6, 6, v8
	v_cmp_le_i32_e64 s[98:99], v6, v0
	s_nop 1
	v_cndmask_b32_e64 v149, 0, v149, s[98:99]
	v_or_b32_e32 v6, 7, v8
	v_cmp_le_i32_e64 s[98:99], v6, v0
	s_nop 1
	v_cndmask_b32_e64 v147, 0, v147, s[98:99]
	v_or_b32_e32 v6, 16, v8
	v_cmp_le_i32_e64 s[98:99], v6, v0
	s_nop 1
	v_cndmask_b32_e64 v151, 0, v151, s[98:99]
	v_or_b32_e32 v6, 17, v8
	v_cmp_le_i32_e64 s[98:99], v6, v0
	s_nop 1
	v_cndmask_b32_e64 v150, 0, v150, s[98:99]
	v_or_b32_e32 v6, 18, v8
	v_cmp_le_i32_e64 s[98:99], v6, v0
	s_nop 1
	v_cndmask_b32_e64 v153, 0, v153, s[98:99]
	v_or_b32_e32 v6, 19, v8
	v_cmp_le_i32_e64 s[98:99], v6, v0
	s_nop 1
	v_cndmask_b32_e64 v152, 0, v152, s[98:99]
	v_or_b32_e32 v6, 20, v8
	v_cmp_le_i32_e64 s[98:99], v6, v0
	s_nop 1
	v_cndmask_b32_e64 v155, 0, v155, s[98:99]
	v_or_b32_e32 v6, 21, v8
	v_cmp_le_i32_e64 s[98:99], v6, v0
	s_nop 1
	v_cndmask_b32_e64 v154, 0, v154, s[98:99]
	v_or_b32_e32 v6, 22, v8
	v_cmp_le_i32_e64 s[98:99], v6, v0
	s_nop 1
	v_cndmask_b32_e64 v157, 0, v157, s[98:99]
	v_or_b32_e32 v6, 23, v8
	v_cmp_le_i32_e64 s[98:99], v6, v0
	s_nop 1
	v_cndmask_b32_e64 v156, 0, v156, s[98:99]

; #define MFMA32(a, b, c) __builtin_amdgcn_mfma_f32_32x32x16_bf16((a), (b), (c), 0, 0, 0)
; DI void a1_task(unsigned char* shm, const bf16_t* prm, const bf16_t* prt, unsigned* mask, int b, int qt, const int tid) {
;     ...
;             for (int hh = 0; hh < 8; ++hh) {
;                 bf16x8 qa[4];
; #pragma unroll
;                 for (int ks = 0; ks < 4; ++ks) qa[ks] = *(const bf16x8*)(qb0 + hh * 128 + 32 * ks);
;                 const float wv = wqs[hh * 32 + r];
;                 asm volatile("s_waitcnt lgkmcnt(0)" ::: "memory");
;                 f32x16 acc;
; #pragma unroll
;                 for (int i = 0; i < 16; ++i) acc[i] = 0.f;
; #pragma unroll
;                 for (int ks = 0; ks < 4; ++ks) acc = MFMA32(kf[ks], qa[ks], acc);
; #pragma unroll
;                 for (int i = 0; i < 16; ++i) idx[i] = fmaf(wv, fmaxf(acc[i], 0.f), idx[i]);
;             }
; #pragma unroll
;             for (int i = 0; i < 16; ++i) {
;                 const int s = s0 + 16 * (i >> 3) + 8 * h + (i & 7);
;                 const unsigned u = __float_as_uint(idx[i] + 0.0f);
;                 const unsigned k = (u & 0x80000000u) ? ~u : (u | 0x80000000u);
;                 key[jt][i] = (s <= t0 + r) ? k : 0u;
;             }
.LBB0_399:
	v_add_u32_e32 v79, s1, v118
	ds_read_b128 v[2:5], v79
	ds_read_b128 v[66:69], v79 offset:32
	ds_read_b128 v[70:73], v79 offset:64
	ds_read_b128 v[74:77], v79 offset:96
	v_add_u32_e32 v80, s1, v135
	s_waitcnt lgkmcnt(3)
	v_mfma_f32_32x32x16_bf16 v[2:17], v[34:37], v[2:5], 0
	ds_read_b32 v78, v80
	s_waitcnt lgkmcnt(0)
	s_addk_i32 s1, 0x100
	s_cmpk_lg_i32 s1, 0x400
	s_waitcnt lgkmcnt(3)
	v_mfma_f32_32x32x16_bf16 v[2:17], v[38:41], v[66:69], v[2:17]
	s_waitcnt lgkmcnt(2)
	v_mfma_f32_32x32x16_bf16 v[2:17], v[42:45], v[70:73], v[2:17]
	s_waitcnt lgkmcnt(1)
	v_mfma_f32_32x32x16_bf16 v[2:17], v[46:49], v[74:77], v[2:17]
	s_nop 11
	v_max_f32_e32 v2, 0, v2
	v_max_f32_e32 v3, 0, v3
	s_waitcnt lgkmcnt(0)
	v_pk_fma_f32 v[64:65], v[78:79], v[2:3], v[64:65] op_sel_hi:[0,1,1]
	v_max_f32_e32 v2, 0, v4
	v_max_f32_e32 v3, 0, v5
	v_pk_fma_f32 v[62:63], v[78:79], v[2:3], v[62:63] op_sel_hi:[0,1,1]
	v_max_f32_e32 v2, 0, v6
	v_max_f32_e32 v3, 0, v7
	v_pk_fma_f32 v[60:61], v[78:79], v[2:3], v[60:61] op_sel_hi:[0,1,1]
	v_max_f32_e32 v2, 0, v8
	v_max_f32_e32 v3, 0, v9
	v_pk_fma_f32 v[58:59], v[78:79], v[2:3], v[58:59] op_sel_hi:[0,1,1]
	v_max_f32_e32 v2, 0, v10
	v_max_f32_e32 v3, 0, v11
	v_pk_fma_f32 v[56:57], v[78:79], v[2:3], v[56:57] op_sel_hi:[0,1,1]
	v_max_f32_e32 v2, 0, v12
	v_max_f32_e32 v3, 0, v13
	v_pk_fma_f32 v[54:55], v[78:79], v[2:3], v[54:55] op_sel_hi:[0,1,1]
	v_max_f32_e32 v2, 0, v14
	v_max_f32_e32 v3, 0, v15
	v_pk_fma_f32 v[52:53], v[78:79], v[2:3], v[52:53] op_sel_hi:[0,1,1]
	v_max_f32_e32 v2, 0, v16
	v_max_f32_e32 v3, 0, v17
	v_pk_fma_f32 v[50:51], v[78:79], v[2:3], v[50:51] op_sel_hi:[0,1,1]
	ds_read_b128 v[2:5], v79 offset:128
	ds_read_b128 v[66:69], v79 offset:160
	ds_read_b128 v[70:73], v79 offset:192
	ds_read_b128 v[74:77], v79 offset:224
	ds_read_b32 v78, v80 offset:128
	s_waitcnt lgkmcnt(4)
	v_mfma_f32_32x32x16_bf16 v[2:17], v[34:37], v[2:5], 0
	s_waitcnt lgkmcnt(0)
	s_waitcnt lgkmcnt(3)
	v_mfma_f32_32x32x16_bf16 v[2:17], v[38:41], v[66:69], v[2:17]
	s_waitcnt lgkmcnt(2)
	v_mfma_f32_32x32x16_bf16 v[2:17], v[42:45], v[70:73], v[2:17]
	s_waitcnt lgkmcnt(1)
	v_mfma_f32_32x32x16_bf16 v[2:17], v[46:49], v[74:77], v[2:17]
	s_nop 11
	v_max_f32_e32 v2, 0, v2
	v_max_f32_e32 v3, 0, v3
	s_waitcnt lgkmcnt(0)
	v_pk_fma_f32 v[64:65], v[78:79], v[2:3], v[64:65] op_sel_hi:[0,1,1]
	v_max_f32_e32 v2, 0, v4
	v_max_f32_e32 v3, 0, v5
	v_pk_fma_f32 v[62:63], v[78:79], v[2:3], v[62:63] op_sel_hi:[0,1,1]
	v_max_f32_e32 v2, 0, v6
	v_max_f32_e32 v3, 0, v7
	v_pk_fma_f32 v[60:61], v[78:79], v[2:3], v[60:61] op_sel_hi:[0,1,1]
	v_max_f32_e32 v2, 0, v8
	v_max_f32_e32 v3, 0, v9
	v_pk_fma_f32 v[58:59], v[78:79], v[2:3], v[58:59] op_sel_hi:[0,1,1]
	v_max_f32_e32 v2, 0, v10
	v_max_f32_e32 v3, 0, v11
	v_pk_fma_f32 v[56:57], v[78:79], v[2:3], v[56:57] op_sel_hi:[0,1,1]
	v_max_f32_e32 v2, 0, v12
	v_max_f32_e32 v3, 0, v13
	v_pk_fma_f32 v[54:55], v[78:79], v[2:3], v[54:55] op_sel_hi:[0,1,1]
	v_max_f32_e32 v2, 0, v14
	v_max_f32_e32 v3, 0, v15
	v_pk_fma_f32 v[52:53], v[78:79], v[2:3], v[52:53] op_sel_hi:[0,1,1]
	v_max_f32_e32 v2, 0, v16
	v_max_f32_e32 v3, 0, v17
	v_pk_fma_f32 v[50:51], v[78:79], v[2:3], v[50:51] op_sel_hi:[0,1,1]
	s_cbranch_scc1 .LBB0_399
	v_pk_add_f32 v[2:3], v[64:65], 0 op_sel_hi:[1,0]
	v_ashrrev_i32_e32 v4, 31, v2
	v_ashrrev_i32_e32 v5, 31, v3
	v_or_b32_e32 v4, 0x80000000, v4
	v_or_b32_e32 v5, 0x80000000, v5
	v_xor_b32_e32 v166, v2, v4
	v_xor_b32_e32 v167, v3, v5
	v_pk_add_f32 v[2:3], v[62:63], 0 op_sel_hi:[1,0]
	v_ashrrev_i32_e32 v4, 31, v2
	v_ashrrev_i32_e32 v5, 31, v3
	v_or_b32_e32 v4, 0x80000000, v4
	v_or_b32_e32 v5, 0x80000000, v5
	v_xor_b32_e32 v159, v2, v4
	v_xor_b32_e32 v158, v3, v5
	v_pk_add_f32 v[2:3], v[60:61], 0 op_sel_hi:[1,0]
	v_ashrrev_i32_e32 v4, 31, v2
	v_ashrrev_i32_e32 v5, 31, v3
	v_or_b32_e32 v4, 0x80000000, v4
	v_or_b32_e32 v5, 0x80000000, v5
	v_xor_b32_e32 v161, v2, v4
	v_xor_b32_e32 v160, v3, v5
	v_pk_add_f32 v[2:3], v[58:59], 0 op_sel_hi:[1,0]
	v_ashrrev_i32_e32 v4, 31, v2
	v_ashrrev_i32_e32 v5, 31, v3
	v_or_b32_e32 v4, 0x80000000, v4
	v_or_b32_e32 v5, 0x80000000, v5
	v_xor_b32_e32 v163, v2, v4
	v_xor_b32_e32 v162, v3, v5
	v_pk_add_f32 v[2:3], v[56:57], 0 op_sel_hi:[1,0]
	v_ashrrev_i32_e32 v4, 31, v2
	v_ashrrev_i32_e32 v5, 31, v3
	v_or_b32_e32 v4, 0x80000000, v4
	v_or_b32_e32 v5, 0x80000000, v5
	v_xor_b32_e32 v165, v2, v4
	v_xor_b32_e32 v164, v3, v5
	v_pk_add_f32 v[2:3], v[54:55], 0 op_sel_hi:[1,0]
	v_ashrrev_i32_e32 v4, 31, v2
	v_ashrrev_i32_e32 v5, 31, v3
	v_or_b32_e32 v4, 0x80000000, v4
	v_or_b32_e32 v5, 0x80000000, v5
	v_xor_b32_e32 v169, v2, v4
	v_xor_b32_e32 v168, v3, v5
	v_pk_add_f32 v[2:3], v[52:53], 0 op_sel_hi:[1,0]
	v_ashrrev_i32_e32 v4, 31, v2
	v_ashrrev_i32_e32 v5, 31, v3
	v_or_b32_e32 v4, 0x80000000, v4
	v_or_b32_e32 v5, 0x80000000, v5
	v_xor_b32_e32 v171, v2, v4
	v_xor_b32_e32 v170, v3, v5
	v_pk_add_f32 v[2:3], v[50:51], 0 op_sel_hi:[1,0]
	v_ashrrev_i32_e32 v4, 31, v2
	v_ashrrev_i32_e32 v5, 31, v3
	v_or_b32_e32 v4, 0x80000000, v4
	v_or_b32_e32 v5, 0x80000000, v5
	v_xor_b32_e32 v173, v2, v4
	v_xor_b32_e32 v172, v3, v5
	s_lshr_b32 s98, s0, 5
	s_cmp_lt_u32 s98, s2
	s_cbranch_scc1 .Lkc_done_399
	v_or_b32_e32 v8, s0, v98
	v_cmp_le_i32_e64 s[98:99], v8, v0
	s_nop 1
	v_cndmask_b32_e64 v166, 0, v166, s[98:99]
	v_or_b32_e32 v6, 1, v8
	v_cmp_le_i32_e64 s[98:99], v6, v0
	s_nop 1
	v_cndmask_b32_e64 v167, 0, v167, s[98:99]
	v_or_b32_e32 v6, 2, v8
	v_cmp_le_i32_e64 s[98:99], v6, v0
	s_nop 1
	v_cndmask_b32_e64 v159, 0, v159, s[98:99]
	v_or_b32_e32 v6, 3, v8
	v_cmp_le_i32_e64 s[98:99], v6, v0
	s_nop 1
	v_cndmask_b32_e64 v158, 0, v158, s[98:99]
	v_or_b32_e32 v6, 4, v8
	v_cmp_le_i32_e64 s[98:99], v6, v0
	s_nop 1
	v_cndmask_b32_e64 v161, 0, v161, s[98:99]
	v_or_b32_e32 v6, 5, v8
	v_cmp_le_i32_e64 s[98:99], v6, v0
	s_nop 1
	v_cndmask_b32_e64 v160, 0, v160, s[98:99]
	v_or_b32_e32 v6, 6, v8
	v_cmp_le_i32_e64 s[98:99], v6, v0
	s_nop 1
	v_cndmask_b32_e64 v163, 0, v163, s[98:99]
	v_or_b32_e32 v6, 7, v8
	v_cmp_le_i32_e64 s[98:99], v6, v0
	s_nop 1
	v_cndmask_b32_e64 v162, 0, v162, s[98:99]
	v_or_b32_e32 v6, 16, v8
	v_cmp_le_i32_e64 s[98:99], v6, v0
	s_nop 1
	v_cndmask_b32_e64 v165, 0, v165, s[98:99]
	v_or_b32_e32 v6, 17, v8
	v_cmp_le_i32_e64 s[98:99], v6, v0
	s_nop 1
	v_cndmask_b32_e64 v164, 0, v164, s[98:99]
	v_or_b32_e32 v6, 18, v8
	v_cmp_le_i32_e64 s[98:99], v6, v0
	s_nop 1
	v_cndmask_b32_e64 v169, 0, v169, s[98:99]
	v_or_b32_e32 v6, 19, v8
	v_cmp_le_i32_e64 s[98:99], v6, v0
	s_nop 1
	v_cndmask_b32_e64 v168, 0, v168, s[98:99]
	v_or_b32_e32 v6, 20, v8
	v_cmp_le_i32_e64 s[98:99], v6, v0
	s_nop 1
	v_cndmask_b32_e64 v171, 0, v171, s[98:99]
	v_or_b32_e32 v6, 21, v8
	v_cmp_le_i32_e64 s[98:99], v6, v0
	s_nop 1
	v_cndmask_b32_e64 v170, 0, v170, s[98:99]
	v_or_b32_e32 v6, 22, v8
	v_cmp_le_i32_e64 s[98:99], v6, v0
	s_nop 1
	v_cndmask_b32_e64 v173, 0, v173, s[98:99]
	v_or_b32_e32 v6, 23, v8
	v_cmp_le_i32_e64 s[98:99], v6, v0
	s_nop 1
	v_cndmask_b32_e64 v172, 0, v172, s[98:99]

; #define MFMA32(a, b, c) __builtin_amdgcn_mfma_f32_32x32x16_bf16((a), (b), (c), 0, 0, 0)
; DI void a1_task(unsigned char* shm, const bf16_t* prm, const bf16_t* prt, unsigned* mask, int b, int qt, const int tid) {
;     ...
;             for (int hh = 0; hh < 8; ++hh) {
;                 bf16x8 qa[4];
; #pragma unroll
;                 for (int ks = 0; ks < 4; ++ks) qa[ks] = *(const bf16x8*)(qb0 + hh * 128 + 32 * ks);
;                 const float wv = wqs[hh * 32 + r];
;                 asm volatile("s_waitcnt lgkmcnt(0)" ::: "memory");
;                 f32x16 acc;
; #pragma unroll
;                 for (int i = 0; i < 16; ++i) acc[i] = 0.f;
; #pragma unroll
;                 for (int ks = 0; ks < 4; ++ks) acc = MFMA32(kf[ks], qa[ks], acc);
; #pragma unroll
;                 for (int i = 0; i < 16; ++i) idx[i] = fmaf(wv, fmaxf(acc[i], 0.f), idx[i]);
;             }
; #pragma unroll
;             for (int i = 0; i < 16; ++i) {
;                 const int s = s0 + 16 * (i >> 3) + 8 * h + (i & 7);
;                 const unsigned u = __float_as_uint(idx[i] + 0.0f);
;                 const unsigned k = (u & 0x80000000u) ? ~u : (u | 0x80000000u);
;                 key[jt][i] = (s <= t0 + r) ? k : 0u;
;             }
.LBB0_408:
	v_add_u32_e32 v95, s1, v118
	ds_read_b128 v[2:5], v95
	ds_read_b128 v[82:85], v95 offset:32
	ds_read_b128 v[86:89], v95 offset:64
	ds_read_b128 v[90:93], v95 offset:96
	v_add_u32_e32 v96, s1, v135
	s_waitcnt lgkmcnt(3)
	v_mfma_f32_32x32x16_bf16 v[2:17], v[34:37], v[2:5], 0
	ds_read_b32 v94, v96
	s_waitcnt lgkmcnt(0)
	s_addk_i32 s1, 0x100
	s_cmpk_lg_i32 s1, 0x400
	s_waitcnt lgkmcnt(3)
	v_mfma_f32_32x32x16_bf16 v[2:17], v[38:41], v[82:85], v[2:17]
	s_waitcnt lgkmcnt(2)
	v_mfma_f32_32x32x16_bf16 v[2:17], v[42:45], v[86:89], v[2:17]
	s_waitcnt lgkmcnt(1)
	v_mfma_f32_32x32x16_bf16 v[2:17], v[46:49], v[90:93], v[2:17]
	s_nop 11
	v_max_f32_e32 v2, 0, v2
	v_max_f32_e32 v3, 0, v3
	s_waitcnt lgkmcnt(0)
	v_pk_fma_f32 v[80:81], v[94:95], v[2:3], v[80:81] op_sel_hi:[0,1,1]
	v_max_f32_e32 v2, 0, v4
	v_max_f32_e32 v3, 0, v5
	v_pk_fma_f32 v[78:79], v[94:95], v[2:3], v[78:79] op_sel_hi:[0,1,1]
	v_max_f32_e32 v2, 0, v6
	v_max_f32_e32 v3, 0, v7
	v_pk_fma_f32 v[76:77], v[94:95], v[2:3], v[76:77] op_sel_hi:[0,1,1]
	v_max_f32_e32 v2, 0, v8
	v_max_f32_e32 v3, 0, v9
	v_pk_fma_f32 v[74:75], v[94:95], v[2:3], v[74:75] op_sel_hi:[0,1,1]
	v_max_f32_e32 v2, 0, v10
	v_max_f32_e32 v3, 0, v11
	v_pk_fma_f32 v[72:73], v[94:95], v[2:3], v[72:73] op_sel_hi:[0,1,1]
	v_max_f32_e32 v2, 0, v12
	v_max_f32_e32 v3, 0, v13
	v_pk_fma_f32 v[70:71], v[94:95], v[2:3], v[70:71] op_sel_hi:[0,1,1]
	v_max_f32_e32 v2, 0, v14
	v_max_f32_e32 v3, 0, v15
	v_pk_fma_f32 v[68:69], v[94:95], v[2:3], v[68:69] op_sel_hi:[0,1,1]
	v_max_f32_e32 v2, 0, v16
	v_max_f32_e32 v3, 0, v17
	v_pk_fma_f32 v[66:67], v[94:95], v[2:3], v[66:67] op_sel_hi:[0,1,1]
	ds_read_b128 v[2:5], v95 offset:128
	ds_read_b128 v[82:85], v95 offset:160
	ds_read_b128 v[86:89], v95 offset:192
	ds_read_b128 v[90:93], v95 offset:224
	ds_read_b32 v94, v96 offset:128
	s_waitcnt lgkmcnt(4)
	v_mfma_f32_32x32x16_bf16 v[2:17], v[34:37], v[2:5], 0
	s_waitcnt lgkmcnt(0)
	s_waitcnt lgkmcnt(3)
	v_mfma_f32_32x32x16_bf16 v[2:17], v[38:41], v[82:85], v[2:17]
	s_waitcnt lgkmcnt(2)
	v_mfma_f32_32x32x16_bf16 v[2:17], v[42:45], v[86:89], v[2:17]
	s_waitcnt lgkmcnt(1)
	v_mfma_f32_32x32x16_bf16 v[2:17], v[46:49], v[90:93], v[2:17]
	s_nop 11
	v_max_f32_e32 v2, 0, v2
	v_max_f32_e32 v3, 0, v3
	s_waitcnt lgkmcnt(0)
	v_pk_fma_f32 v[80:81], v[94:95], v[2:3], v[80:81] op_sel_hi:[0,1,1]
	v_max_f32_e32 v2, 0, v4
	v_max_f32_e32 v3, 0, v5
	v_pk_fma_f32 v[78:79], v[94:95], v[2:3], v[78:79] op_sel_hi:[0,1,1]
	v_max_f32_e32 v2, 0, v6
	v_max_f32_e32 v3, 0, v7
	v_pk_fma_f32 v[76:77], v[94:95], v[2:3], v[76:77] op_sel_hi:[0,1,1]
	v_max_f32_e32 v2, 0, v8
	v_max_f32_e32 v3, 0, v9
	v_pk_fma_f32 v[74:75], v[94:95], v[2:3], v[74:75] op_sel_hi:[0,1,1]
	v_max_f32_e32 v2, 0, v10
	v_max_f32_e32 v3, 0, v11
	v_pk_fma_f32 v[72:73], v[94:95], v[2:3], v[72:73] op_sel_hi:[0,1,1]
	v_max_f32_e32 v2, 0, v12
	v_max_f32_e32 v3, 0, v13
	v_pk_fma_f32 v[70:71], v[94:95], v[2:3], v[70:71] op_sel_hi:[0,1,1]
	v_max_f32_e32 v2, 0, v14
	v_max_f32_e32 v3, 0, v15
	v_pk_fma_f32 v[68:69], v[94:95], v[2:3], v[68:69] op_sel_hi:[0,1,1]
	v_max_f32_e32 v2, 0, v16
	v_max_f32_e32 v3, 0, v17
	v_pk_fma_f32 v[66:67], v[94:95], v[2:3], v[66:67] op_sel_hi:[0,1,1]
	s_cbranch_scc1 .LBB0_408
	v_pk_add_f32 v[2:3], v[80:81], 0 op_sel_hi:[1,0]
	v_ashrrev_i32_e32 v4, 31, v2
	v_ashrrev_i32_e32 v5, 31, v3
	v_or_b32_e32 v4, 0x80000000, v4
	v_or_b32_e32 v5, 0x80000000, v5
	v_xor_b32_e32 v175, v2, v4
	v_xor_b32_e32 v174, v3, v5
	v_pk_add_f32 v[2:3], v[78:79], 0 op_sel_hi:[1,0]
	v_ashrrev_i32_e32 v4, 31, v2
	v_ashrrev_i32_e32 v5, 31, v3
	v_or_b32_e32 v4, 0x80000000, v4
	v_or_b32_e32 v5, 0x80000000, v5
	v_xor_b32_e32 v177, v2, v4
	v_xor_b32_e32 v176, v3, v5
	v_pk_add_f32 v[2:3], v[76:77], 0 op_sel_hi:[1,0]
	v_ashrrev_i32_e32 v4, 31, v2
	v_ashrrev_i32_e32 v5, 31, v3
	v_or_b32_e32 v4, 0x80000000, v4
	v_or_b32_e32 v5, 0x80000000, v5
	v_xor_b32_e32 v179, v2, v4
	v_xor_b32_e32 v178, v3, v5
	v_pk_add_f32 v[2:3], v[74:75], 0 op_sel_hi:[1,0]
	v_ashrrev_i32_e32 v4, 31, v2
	v_ashrrev_i32_e32 v5, 31, v3
	v_or_b32_e32 v4, 0x80000000, v4
	v_or_b32_e32 v5, 0x80000000, v5
	v_xor_b32_e32 v181, v2, v4
	v_xor_b32_e32 v180, v3, v5
	v_pk_add_f32 v[2:3], v[72:73], 0 op_sel_hi:[1,0]
	v_ashrrev_i32_e32 v4, 31, v2
	v_ashrrev_i32_e32 v5, 31, v3
	v_or_b32_e32 v4, 0x80000000, v4
	v_or_b32_e32 v5, 0x80000000, v5
	v_xor_b32_e32 v183, v2, v4
	v_xor_b32_e32 v182, v3, v5
	v_pk_add_f32 v[2:3], v[70:71], 0 op_sel_hi:[1,0]
	v_ashrrev_i32_e32 v4, 31, v2
	v_ashrrev_i32_e32 v5, 31, v3
	v_or_b32_e32 v4, 0x80000000, v4
	v_or_b32_e32 v5, 0x80000000, v5
	v_xor_b32_e32 v185, v2, v4
	v_xor_b32_e32 v184, v3, v5
	v_pk_add_f32 v[2:3], v[68:69], 0 op_sel_hi:[1,0]
	v_ashrrev_i32_e32 v4, 31, v2
	v_ashrrev_i32_e32 v5, 31, v3
	v_or_b32_e32 v4, 0x80000000, v4
	v_or_b32_e32 v5, 0x80000000, v5
	v_xor_b32_e32 v187, v2, v4
	v_xor_b32_e32 v186, v3, v5
	v_pk_add_f32 v[2:3], v[66:67], 0 op_sel_hi:[1,0]
	v_ashrrev_i32_e32 v4, 31, v2
	v_ashrrev_i32_e32 v5, 31, v3
	v_or_b32_e32 v4, 0x80000000, v4
	v_or_b32_e32 v5, 0x80000000, v5
	v_xor_b32_e32 v189, v2, v4
	v_xor_b32_e32 v188, v3, v5
	s_lshr_b32 s98, s0, 5
	s_cmp_lt_u32 s98, s2
	s_cbranch_scc1 .Lkc_done_408
	v_or_b32_e32 v8, s0, v98
	v_cmp_le_i32_e64 s[98:99], v8, v0
	s_nop 1
	v_cndmask_b32_e64 v175, 0, v175, s[98:99]
	v_or_b32_e32 v6, 1, v8
	v_cmp_le_i32_e64 s[98:99], v6, v0
	s_nop 1
	v_cndmask_b32_e64 v174, 0, v174, s[98:99]
	v_or_b32_e32 v6, 2, v8
	v_cmp_le_i32_e64 s[98:99], v6, v0
	s_nop 1
	v_cndmask_b32_e64 v177, 0, v177, s[98:99]
	v_or_b32_e32 v6, 3, v8
	v_cmp_le_i32_e64 s[98:99], v6, v0
	s_nop 1
	v_cndmask_b32_e64 v176, 0, v176, s[98:99]
	v_or_b32_e32 v6, 4, v8
	v_cmp_le_i32_e64 s[98:99], v6, v0
	s_nop 1
	v_cndmask_b32_e64 v179, 0, v179, s[98:99]
	v_or_b32_e32 v6, 5, v8
	v_cmp_le_i32_e64 s[98:99], v6, v0
	s_nop 1
	v_cndmask_b32_e64 v178, 0, v178, s[98:99]
	v_or_b32_e32 v6, 6, v8
	v_cmp_le_i32_e64 s[98:99], v6, v0
	s_nop 1
	v_cndmask_b32_e64 v181, 0, v181, s[98:99]
	v_or_b32_e32 v6, 7, v8
	v_cmp_le_i32_e64 s[98:99], v6, v0
	s_nop 1
	v_cndmask_b32_e64 v180, 0, v180, s[98:99]
	v_or_b32_e32 v6, 16, v8
	v_cmp_le_i32_e64 s[98:99], v6, v0
	s_nop 1
	v_cndmask_b32_e64 v183, 0, v183, s[98:99]
	v_or_b32_e32 v6, 17, v8
	v_cmp_le_i32_e64 s[98:99], v6, v0
	s_nop 1
	v_cndmask_b32_e64 v182, 0, v182, s[98:99]
	v_or_b32_e32 v6, 18, v8
	v_cmp_le_i32_e64 s[98:99], v6, v0
	s_nop 1
	v_cndmask_b32_e64 v185, 0, v185, s[98:99]
	v_or_b32_e32 v6, 19, v8
	v_cmp_le_i32_e64 s[98:99], v6, v0
	s_nop 1
	v_cndmask_b32_e64 v184, 0, v184, s[98:99]
	v_or_b32_e32 v6, 20, v8
	v_cmp_le_i32_e64 s[98:99], v6, v0
	s_nop 1
	v_cndmask_b32_e64 v187, 0, v187, s[98:99]
	v_or_b32_e32 v6, 21, v8
	v_cmp_le_i32_e64 s[98:99], v6, v0
	s_nop 1
	v_cndmask_b32_e64 v186, 0, v186, s[98:99]
	v_or_b32_e32 v6, 22, v8
	v_cmp_le_i32_e64 s[98:99], v6, v0
	s_nop 1
	v_cndmask_b32_e64 v189, 0, v189, s[98:99]
	v_or_b32_e32 v6, 23, v8
	v_cmp_le_i32_e64 s[98:99], v6, v0
	s_nop 1
	v_cndmask_b32_e64 v188, 0, v188, s[98:99]

; #define MFMA32(a, b, c) __builtin_amdgcn_mfma_f32_32x32x16_bf16((a), (b), (c), 0, 0, 0)
; DI void a1_task(unsigned char* shm, const bf16_t* prm, const bf16_t* prt, unsigned* mask, int b, int qt, const int tid) {
;     ...
;             for (int hh = 0; hh < 8; ++hh) {
;                 bf16x8 qa[4];
; #pragma unroll
;                 for (int ks = 0; ks < 4; ++ks) qa[ks] = *(const bf16x8*)(qb0 + hh * 128 + 32 * ks);
;                 const float wv = wqs[hh * 32 + r];
;                 asm volatile("s_waitcnt lgkmcnt(0)" ::: "memory");
;                 f32x16 acc;
; #pragma unroll
;                 for (int i = 0; i < 16; ++i) acc[i] = 0.f;
; #pragma unroll
;                 for (int ks = 0; ks < 4; ++ks) acc = MFMA32(kf[ks], qa[ks], acc);
; #pragma unroll
;                 for (int i = 0; i < 16; ++i) idx[i] = fmaf(wv, fmaxf(acc[i], 0.f), idx[i]);
;             }
; #pragma unroll
;             for (int i = 0; i < 16; ++i) {
;                 const int s = s0 + 16 * (i >> 3) + 8 * h + (i & 7);
;                 const unsigned u = __float_as_uint(idx[i] + 0.0f);
;                 const unsigned k = (u & 0x80000000u) ? ~u : (u | 0x80000000u);
;                 key[jt][i] = (s <= t0 + r) ? k : 0u;
;             }
.LBB0_418:
	v_add_u32_e32 v95, s1, v118
	ds_read_b128 v[2:5], v95
	ds_read_b128 v[70:73], v95 offset:32
	ds_read_b128 v[78:81], v95 offset:64
	ds_read_b128 v[86:89], v95 offset:96
	v_add_u32_e32 v96, s1, v135
	s_waitcnt lgkmcnt(3)
	v_mfma_f32_32x32x16_bf16 v[2:17], v[66:69], v[2:5], 0
	ds_read_b32 v94, v96
	s_waitcnt lgkmcnt(0)
	s_addk_i32 s1, 0x100
	s_cmpk_lg_i32 s1, 0x400
	s_waitcnt lgkmcnt(3)
	v_mfma_f32_32x32x16_bf16 v[2:17], v[74:77], v[70:73], v[2:17]
	s_waitcnt lgkmcnt(2)
	v_mfma_f32_32x32x16_bf16 v[2:17], v[82:85], v[78:81], v[2:17]
	s_waitcnt lgkmcnt(1)
	v_mfma_f32_32x32x16_bf16 v[2:17], v[90:93], v[86:89], v[2:17]
	s_nop 11
	v_max_f32_e32 v2, 0, v2
	v_max_f32_e32 v3, 0, v3
	s_waitcnt lgkmcnt(0)
	v_pk_fma_f32 v[32:33], v[94:95], v[2:3], v[32:33] op_sel_hi:[0,1,1]
	v_max_f32_e32 v2, 0, v4
	v_max_f32_e32 v3, 0, v5
	v_pk_fma_f32 v[30:31], v[94:95], v[2:3], v[30:31] op_sel_hi:[0,1,1]
	v_max_f32_e32 v2, 0, v6
	v_max_f32_e32 v3, 0, v7
	v_pk_fma_f32 v[28:29], v[94:95], v[2:3], v[28:29] op_sel_hi:[0,1,1]
	v_max_f32_e32 v2, 0, v8
	v_max_f32_e32 v3, 0, v9
	v_pk_fma_f32 v[26:27], v[94:95], v[2:3], v[26:27] op_sel_hi:[0,1,1]
	v_max_f32_e32 v2, 0, v10
	v_max_f32_e32 v3, 0, v11
	v_pk_fma_f32 v[24:25], v[94:95], v[2:3], v[24:25] op_sel_hi:[0,1,1]
	v_max_f32_e32 v2, 0, v12
	v_max_f32_e32 v3, 0, v13
	v_pk_fma_f32 v[22:23], v[94:95], v[2:3], v[22:23] op_sel_hi:[0,1,1]
	v_max_f32_e32 v2, 0, v14
	v_max_f32_e32 v3, 0, v15
	v_pk_fma_f32 v[20:21], v[94:95], v[2:3], v[20:21] op_sel_hi:[0,1,1]
	v_max_f32_e32 v2, 0, v16
	v_max_f32_e32 v3, 0, v17
	v_pk_fma_f32 v[18:19], v[94:95], v[2:3], v[18:19] op_sel_hi:[0,1,1]
	ds_read_b128 v[2:5], v95 offset:128
	ds_read_b128 v[70:73], v95 offset:160
	ds_read_b128 v[78:81], v95 offset:192
	ds_read_b128 v[86:89], v95 offset:224
	ds_read_b32 v94, v96 offset:128
	s_waitcnt lgkmcnt(4)
	v_mfma_f32_32x32x16_bf16 v[2:17], v[66:69], v[2:5], 0
	s_waitcnt lgkmcnt(0)
	s_waitcnt lgkmcnt(3)
	v_mfma_f32_32x32x16_bf16 v[2:17], v[74:77], v[70:73], v[2:17]
	s_waitcnt lgkmcnt(2)
	v_mfma_f32_32x32x16_bf16 v[2:17], v[82:85], v[78:81], v[2:17]
	s_waitcnt lgkmcnt(1)
	v_mfma_f32_32x32x16_bf16 v[2:17], v[90:93], v[86:89], v[2:17]
	s_nop 11
	v_max_f32_e32 v2, 0, v2
	v_max_f32_e32 v3, 0, v3
	s_waitcnt lgkmcnt(0)
	v_pk_fma_f32 v[32:33], v[94:95], v[2:3], v[32:33] op_sel_hi:[0,1,1]
	v_max_f32_e32 v2, 0, v4
	v_max_f32_e32 v3, 0, v5
	v_pk_fma_f32 v[30:31], v[94:95], v[2:3], v[30:31] op_sel_hi:[0,1,1]
	v_max_f32_e32 v2, 0, v6
	v_max_f32_e32 v3, 0, v7
	v_pk_fma_f32 v[28:29], v[94:95], v[2:3], v[28:29] op_sel_hi:[0,1,1]
	v_max_f32_e32 v2, 0, v8
	v_max_f32_e32 v3, 0, v9
	v_pk_fma_f32 v[26:27], v[94:95], v[2:3], v[26:27] op_sel_hi:[0,1,1]
	v_max_f32_e32 v2, 0, v10
	v_max_f32_e32 v3, 0, v11
	v_pk_fma_f32 v[24:25], v[94:95], v[2:3], v[24:25] op_sel_hi:[0,1,1]
	v_max_f32_e32 v2, 0, v12
	v_max_f32_e32 v3, 0, v13
	v_pk_fma_f32 v[22:23], v[94:95], v[2:3], v[22:23] op_sel_hi:[0,1,1]
	v_max_f32_e32 v2, 0, v14
	v_max_f32_e32 v3, 0, v15
	v_pk_fma_f32 v[20:21], v[94:95], v[2:3], v[20:21] op_sel_hi:[0,1,1]
	v_max_f32_e32 v2, 0, v16
	v_max_f32_e32 v3, 0, v17
	v_pk_fma_f32 v[18:19], v[94:95], v[2:3], v[18:19] op_sel_hi:[0,1,1]
	s_cbranch_scc1 .LBB0_418
	v_pk_add_f32 v[2:3], v[32:33], 0 op_sel_hi:[1,0]
	v_ashrrev_i32_e32 v4, 31, v2
	v_ashrrev_i32_e32 v5, 31, v3
	v_or_b32_e32 v4, 0x80000000, v4
	v_or_b32_e32 v5, 0x80000000, v5
	v_xor_b32_e32 v191, v2, v4
	v_xor_b32_e32 v190, v3, v5
	v_pk_add_f32 v[2:3], v[30:31], 0 op_sel_hi:[1,0]
	v_ashrrev_i32_e32 v4, 31, v2
	v_ashrrev_i32_e32 v5, 31, v3
	v_or_b32_e32 v4, 0x80000000, v4
	v_or_b32_e32 v5, 0x80000000, v5
	v_xor_b32_e32 v193, v2, v4
	v_xor_b32_e32 v192, v3, v5
	v_pk_add_f32 v[2:3], v[28:29], 0 op_sel_hi:[1,0]
	v_ashrrev_i32_e32 v4, 31, v2
	v_ashrrev_i32_e32 v5, 31, v3
	v_or_b32_e32 v4, 0x80000000, v4
	v_or_b32_e32 v5, 0x80000000, v5
	v_xor_b32_e32 v212, v2, v4
	v_xor_b32_e32 v211, v3, v5
	v_pk_add_f32 v[2:3], v[26:27], 0 op_sel_hi:[1,0]
	v_ashrrev_i32_e32 v4, 31, v2
	v_ashrrev_i32_e32 v5, 31, v3
	v_or_b32_e32 v4, 0x80000000, v4
	v_or_b32_e32 v5, 0x80000000, v5
	v_xor_b32_e32 v214, v2, v4
	v_xor_b32_e32 v213, v3, v5
	v_pk_add_f32 v[2:3], v[24:25], 0 op_sel_hi:[1,0]
	v_ashrrev_i32_e32 v4, 31, v2
	v_ashrrev_i32_e32 v5, 31, v3
	v_or_b32_e32 v4, 0x80000000, v4
	v_or_b32_e32 v5, 0x80000000, v5
	v_xor_b32_e32 v216, v2, v4
	v_xor_b32_e32 v215, v3, v5
	v_pk_add_f32 v[2:3], v[22:23], 0 op_sel_hi:[1,0]
	v_ashrrev_i32_e32 v4, 31, v2
	v_ashrrev_i32_e32 v5, 31, v3
	v_or_b32_e32 v4, 0x80000000, v4
	v_or_b32_e32 v5, 0x80000000, v5
	v_xor_b32_e32 v218, v2, v4
	v_xor_b32_e32 v217, v3, v5
	v_pk_add_f32 v[2:3], v[20:21], 0 op_sel_hi:[1,0]
	v_ashrrev_i32_e32 v4, 31, v2
	v_ashrrev_i32_e32 v5, 31, v3
	v_or_b32_e32 v4, 0x80000000, v4
	v_or_b32_e32 v5, 0x80000000, v5
	v_xor_b32_e32 v220, v2, v4
	v_xor_b32_e32 v219, v3, v5
	v_pk_add_f32 v[2:3], v[18:19], 0 op_sel_hi:[1,0]
	v_ashrrev_i32_e32 v4, 31, v2
	v_ashrrev_i32_e32 v5, 31, v3
	v_or_b32_e32 v4, 0x80000000, v4
	v_or_b32_e32 v5, 0x80000000, v5
	v_xor_b32_e32 v222, v2, v4
	v_xor_b32_e32 v221, v3, v5
	s_lshr_b32 s98, s0, 5
	s_cmp_lt_u32 s98, s2
	s_cbranch_scc1 .Lkc_done_418
	v_or_b32_e32 v8, s0, v98
	v_cmp_le_i32_e64 s[98:99], v8, v0
	s_nop 1
	v_cndmask_b32_e64 v191, 0, v191, s[98:99]
	v_or_b32_e32 v6, 1, v8
	v_cmp_le_i32_e64 s[98:99], v6, v0
	s_nop 1
	v_cndmask_b32_e64 v190, 0, v190, s[98:99]
	v_or_b32_e32 v6, 2, v8
	v_cmp_le_i32_e64 s[98:99], v6, v0
	s_nop 1
	v_cndmask_b32_e64 v193, 0, v193, s[98:99]
	v_or_b32_e32 v6, 3, v8
	v_cmp_le_i32_e64 s[98:99], v6, v0
	s_nop 1
	v_cndmask_b32_e64 v192, 0, v192, s[98:99]
	v_or_b32_e32 v6, 4, v8
	v_cmp_le_i32_e64 s[98:99], v6, v0
	s_nop 1
	v_cndmask_b32_e64 v212, 0, v212, s[98:99]
	v_or_b32_e32 v6, 5, v8
	v_cmp_le_i32_e64 s[98:99], v6, v0
	s_nop 1
	v_cndmask_b32_e64 v211, 0, v211, s[98:99]
	v_or_b32_e32 v6, 6, v8
	v_cmp_le_i32_e64 s[98:99], v6, v0
	s_nop 1
	v_cndmask_b32_e64 v214, 0, v214, s[98:99]
	v_or_b32_e32 v6, 7, v8
	v_cmp_le_i32_e64 s[98:99], v6, v0
	s_nop 1
	v_cndmask_b32_e64 v213, 0, v213, s[98:99]
	v_or_b32_e32 v6, 16, v8
	v_cmp_le_i32_e64 s[98:99], v6, v0
	s_nop 1
	v_cndmask_b32_e64 v216, 0, v216, s[98:99]
	v_or_b32_e32 v6, 17, v8
	v_cmp_le_i32_e64 s[98:99], v6, v0
	s_nop 1
	v_cndmask_b32_e64 v215, 0, v215, s[98:99]
	v_or_b32_e32 v6, 18, v8
	v_cmp_le_i32_e64 s[98:99], v6, v0
	s_nop 1
	v_cndmask_b32_e64 v218, 0, v218, s[98:99]
	v_or_b32_e32 v6, 19, v8
	v_cmp_le_i32_e64 s[98:99], v6, v0
	s_nop 1
	v_cndmask_b32_e64 v217, 0, v217, s[98:99]
	v_or_b32_e32 v6, 20, v8
	v_cmp_le_i32_e64 s[98:99], v6, v0
	s_nop 1
	v_cndmask_b32_e64 v220, 0, v220, s[98:99]
	v_or_b32_e32 v6, 21, v8
	v_cmp_le_i32_e64 s[98:99], v6, v0
	s_nop 1
	v_cndmask_b32_e64 v219, 0, v219, s[98:99]
	v_or_b32_e32 v6, 22, v8
	v_cmp_le_i32_e64 s[98:99], v6, v0
	s_nop 1
	v_cndmask_b32_e64 v222, 0, v222, s[98:99]
	v_or_b32_e32 v6, 23, v8
	v_cmp_le_i32_e64 s[98:99], v6, v0
	s_nop 1
	v_cndmask_b32_e64 v221, 0, v221, s[98:99]

; #define MFMA32(a, b, c) __builtin_amdgcn_mfma_f32_32x32x16_bf16((a), (b), (c), 0, 0, 0)
; DI void a1_task(unsigned char* shm, const bf16_t* prm, const bf16_t* prt, unsigned* mask, int b, int qt, const int tid) {
;     ...
;             for (int hh = 0; hh < 8; ++hh) {
;                 bf16x8 qa[4];
; #pragma unroll
;                 for (int ks = 0; ks < 4; ++ks) qa[ks] = *(const bf16x8*)(qb0 + hh * 128 + 32 * ks);
;                 const float wv = wqs[hh * 32 + r];
;                 asm volatile("s_waitcnt lgkmcnt(0)" ::: "memory");
;                 f32x16 acc;
; #pragma unroll
;                 for (int i = 0; i < 16; ++i) acc[i] = 0.f;
; #pragma unroll
;                 for (int ks = 0; ks < 4; ++ks) acc = MFMA32(kf[ks], qa[ks], acc);
; #pragma unroll
;                 for (int i = 0; i < 16; ++i) idx[i] = fmaf(wv, fmaxf(acc[i], 0.f), idx[i]);
;             }
; #pragma unroll
;             for (int i = 0; i < 16; ++i) {
;                 const int s = s0 + 16 * (i >> 3) + 8 * h + (i & 7);
;                 const unsigned u = __float_as_uint(idx[i] + 0.0f);
;                 const unsigned k = (u & 0x80000000u) ? ~u : (u | 0x80000000u);
;                 key[jt][i] = (s <= t0 + r) ? k : 0u;
;             }
.LBB0_428:
	v_add_u32_e32 v91, s1, v118
	ds_read_b128 v[2:5], v91
	ds_read_b128 v[66:69], v91 offset:32
	ds_read_b128 v[74:77], v91 offset:64
	ds_read_b128 v[82:85], v91 offset:96
	v_add_u32_e32 v92, s1, v135
	s_waitcnt lgkmcnt(3)
	v_mfma_f32_32x32x16_bf16 v[2:17], v[70:73], v[2:5], 0
	ds_read_b32 v90, v92
	s_waitcnt lgkmcnt(0)
	s_addk_i32 s1, 0x100
	s_cmpk_lg_i32 s1, 0x400
	s_waitcnt lgkmcnt(3)
	v_mfma_f32_32x32x16_bf16 v[2:17], v[78:81], v[66:69], v[2:17]
	s_waitcnt lgkmcnt(2)
	v_mfma_f32_32x32x16_bf16 v[2:17], v[86:89], v[74:77], v[2:17]
	s_waitcnt lgkmcnt(1)
	v_mfma_f32_32x32x16_bf16 v[2:17], v[94:97], v[82:85], v[2:17]
	s_nop 11
	v_max_f32_e32 v2, 0, v2
	v_max_f32_e32 v3, 0, v3
	s_waitcnt lgkmcnt(0)
	v_pk_fma_f32 v[64:65], v[90:91], v[2:3], v[64:65] op_sel_hi:[0,1,1]
	v_max_f32_e32 v2, 0, v4
	v_max_f32_e32 v3, 0, v5
	v_pk_fma_f32 v[62:63], v[90:91], v[2:3], v[62:63] op_sel_hi:[0,1,1]
	v_max_f32_e32 v2, 0, v6
	v_max_f32_e32 v3, 0, v7
	v_pk_fma_f32 v[60:61], v[90:91], v[2:3], v[60:61] op_sel_hi:[0,1,1]
	v_max_f32_e32 v2, 0, v8
	v_max_f32_e32 v3, 0, v9
	v_pk_fma_f32 v[58:59], v[90:91], v[2:3], v[58:59] op_sel_hi:[0,1,1]
	v_max_f32_e32 v2, 0, v10
	v_max_f32_e32 v3, 0, v11
	v_pk_fma_f32 v[56:57], v[90:91], v[2:3], v[56:57] op_sel_hi:[0,1,1]
	v_max_f32_e32 v2, 0, v12
	v_max_f32_e32 v3, 0, v13
	v_pk_fma_f32 v[54:55], v[90:91], v[2:3], v[54:55] op_sel_hi:[0,1,1]
	v_max_f32_e32 v2, 0, v14
	v_max_f32_e32 v3, 0, v15
	v_pk_fma_f32 v[52:53], v[90:91], v[2:3], v[52:53] op_sel_hi:[0,1,1]
	v_max_f32_e32 v2, 0, v16
	v_max_f32_e32 v3, 0, v17
	v_pk_fma_f32 v[50:51], v[90:91], v[2:3], v[50:51] op_sel_hi:[0,1,1]
	ds_read_b128 v[2:5], v91 offset:128
	ds_read_b128 v[66:69], v91 offset:160
	ds_read_b128 v[74:77], v91 offset:192
	ds_read_b128 v[82:85], v91 offset:224
	ds_read_b32 v90, v92 offset:128
	s_waitcnt lgkmcnt(4)
	v_mfma_f32_32x32x16_bf16 v[2:17], v[70:73], v[2:5], 0
	s_waitcnt lgkmcnt(0)
	s_waitcnt lgkmcnt(3)
	v_mfma_f32_32x32x16_bf16 v[2:17], v[78:81], v[66:69], v[2:17]
	s_waitcnt lgkmcnt(2)
	v_mfma_f32_32x32x16_bf16 v[2:17], v[86:89], v[74:77], v[2:17]
	s_waitcnt lgkmcnt(1)
	v_mfma_f32_32x32x16_bf16 v[2:17], v[94:97], v[82:85], v[2:17]
	s_nop 11
	v_max_f32_e32 v2, 0, v2
	v_max_f32_e32 v3, 0, v3
	s_waitcnt lgkmcnt(0)
	v_pk_fma_f32 v[64:65], v[90:91], v[2:3], v[64:65] op_sel_hi:[0,1,1]
	v_max_f32_e32 v2, 0, v4
	v_max_f32_e32 v3, 0, v5
	v_pk_fma_f32 v[62:63], v[90:91], v[2:3], v[62:63] op_sel_hi:[0,1,1]
	v_max_f32_e32 v2, 0, v6
	v_max_f32_e32 v3, 0, v7
	v_pk_fma_f32 v[60:61], v[90:91], v[2:3], v[60:61] op_sel_hi:[0,1,1]
	v_max_f32_e32 v2, 0, v8
	v_max_f32_e32 v3, 0, v9
	v_pk_fma_f32 v[58:59], v[90:91], v[2:3], v[58:59] op_sel_hi:[0,1,1]
	v_max_f32_e32 v2, 0, v10
	v_max_f32_e32 v3, 0, v11
	v_pk_fma_f32 v[56:57], v[90:91], v[2:3], v[56:57] op_sel_hi:[0,1,1]
	v_max_f32_e32 v2, 0, v12
	v_max_f32_e32 v3, 0, v13
	v_pk_fma_f32 v[54:55], v[90:91], v[2:3], v[54:55] op_sel_hi:[0,1,1]
	v_max_f32_e32 v2, 0, v14
	v_max_f32_e32 v3, 0, v15
	v_pk_fma_f32 v[52:53], v[90:91], v[2:3], v[52:53] op_sel_hi:[0,1,1]
	v_max_f32_e32 v2, 0, v16
	v_max_f32_e32 v3, 0, v17
	v_pk_fma_f32 v[50:51], v[90:91], v[2:3], v[50:51] op_sel_hi:[0,1,1]
	s_cbranch_scc1 .LBB0_428
	v_pk_add_f32 v[2:3], v[64:65], 0 op_sel_hi:[1,0]
	v_ashrrev_i32_e32 v4, 31, v2
	v_ashrrev_i32_e32 v5, 31, v3
	v_or_b32_e32 v4, 0x80000000, v4
	v_or_b32_e32 v5, 0x80000000, v5
	v_xor_b32_e32 v83, v2, v4
	v_xor_b32_e32 v82, v3, v5
	v_pk_add_f32 v[2:3], v[62:63], 0 op_sel_hi:[1,0]
	v_ashrrev_i32_e32 v4, 31, v2
	v_ashrrev_i32_e32 v5, 31, v3
	v_or_b32_e32 v4, 0x80000000, v4
	v_or_b32_e32 v5, 0x80000000, v5
	v_xor_b32_e32 v85, v2, v4
	v_xor_b32_e32 v84, v3, v5
	v_pk_add_f32 v[2:3], v[60:61], 0 op_sel_hi:[1,0]
	v_ashrrev_i32_e32 v4, 31, v2
	v_ashrrev_i32_e32 v5, 31, v3
	v_or_b32_e32 v4, 0x80000000, v4
	v_or_b32_e32 v5, 0x80000000, v5
	v_xor_b32_e32 v91, v2, v4
	v_xor_b32_e32 v90, v3, v5
	v_pk_add_f32 v[2:3], v[58:59], 0 op_sel_hi:[1,0]
	v_ashrrev_i32_e32 v4, 31, v2
	v_ashrrev_i32_e32 v5, 31, v3
	v_or_b32_e32 v4, 0x80000000, v4
	v_or_b32_e32 v5, 0x80000000, v5
	v_xor_b32_e32 v93, v2, v4
	v_xor_b32_e32 v92, v3, v5
	v_pk_add_f32 v[2:3], v[56:57], 0 op_sel_hi:[1,0]
	v_ashrrev_i32_e32 v4, 31, v2
	v_ashrrev_i32_e32 v5, 31, v3
	v_or_b32_e32 v4, 0x80000000, v4
	v_or_b32_e32 v5, 0x80000000, v5
	v_xor_b32_e32 v224, v2, v4
	v_xor_b32_e32 v223, v3, v5
	v_pk_add_f32 v[2:3], v[54:55], 0 op_sel_hi:[1,0]
	v_ashrrev_i32_e32 v4, 31, v2
	v_ashrrev_i32_e32 v5, 31, v3
	v_or_b32_e32 v4, 0x80000000, v4
	v_or_b32_e32 v5, 0x80000000, v5
	v_xor_b32_e32 v226, v2, v4
	v_xor_b32_e32 v225, v3, v5
	v_pk_add_f32 v[2:3], v[52:53], 0 op_sel_hi:[1,0]
	v_ashrrev_i32_e32 v4, 31, v2
	v_ashrrev_i32_e32 v5, 31, v3
	v_or_b32_e32 v4, 0x80000000, v4
	v_or_b32_e32 v5, 0x80000000, v5
	v_xor_b32_e32 v228, v2, v4
	v_xor_b32_e32 v227, v3, v5
	v_pk_add_f32 v[2:3], v[50:51], 0 op_sel_hi:[1,0]
	v_ashrrev_i32_e32 v4, 31, v2
	v_ashrrev_i32_e32 v5, 31, v3
	v_or_b32_e32 v4, 0x80000000, v4
	v_or_b32_e32 v5, 0x80000000, v5
	v_xor_b32_e32 v230, v2, v4
	v_xor_b32_e32 v229, v3, v5
	s_lshr_b32 s98, s0, 5
	s_cmp_lt_u32 s98, s2
	s_cbranch_scc1 .Lkc_done_428
	v_or_b32_e32 v8, s0, v98
	v_cmp_le_i32_e64 s[98:99], v8, v0
	s_nop 1
	v_cndmask_b32_e64 v83, 0, v83, s[98:99]
	v_or_b32_e32 v6, 1, v8
	v_cmp_le_i32_e64 s[98:99], v6, v0
	s_nop 1
	v_cndmask_b32_e64 v82, 0, v82, s[98:99]
	v_or_b32_e32 v6, 2, v8
	v_cmp_le_i32_e64 s[98:99], v6, v0
	s_nop 1
	v_cndmask_b32_e64 v85, 0, v85, s[98:99]
	v_or_b32_e32 v6, 3, v8
	v_cmp_le_i32_e64 s[98:99], v6, v0
	s_nop 1
	v_cndmask_b32_e64 v84, 0, v84, s[98:99]
	v_or_b32_e32 v6, 4, v8
	v_cmp_le_i32_e64 s[98:99], v6, v0
	s_nop 1
	v_cndmask_b32_e64 v91, 0, v91, s[98:99]
	v_or_b32_e32 v6, 5, v8
	v_cmp_le_i32_e64 s[98:99], v6, v0
	s_nop 1
	v_cndmask_b32_e64 v90, 0, v90, s[98:99]
	v_or_b32_e32 v6, 6, v8
	v_cmp_le_i32_e64 s[98:99], v6, v0
	s_nop 1
	v_cndmask_b32_e64 v93, 0, v93, s[98:99]
	v_or_b32_e32 v6, 7, v8
	v_cmp_le_i32_e64 s[98:99], v6, v0
	s_nop 1
	v_cndmask_b32_e64 v92, 0, v92, s[98:99]
	v_or_b32_e32 v6, 16, v8
	v_cmp_le_i32_e64 s[98:99], v6, v0
	s_nop 1
	v_cndmask_b32_e64 v224, 0, v224, s[98:99]
	v_or_b32_e32 v6, 17, v8
	v_cmp_le_i32_e64 s[98:99], v6, v0
	s_nop 1
	v_cndmask_b32_e64 v223, 0, v223, s[98:99]
	v_or_b32_e32 v6, 18, v8
	v_cmp_le_i32_e64 s[98:99], v6, v0
	s_nop 1
	v_cndmask_b32_e64 v226, 0, v226, s[98:99]
	v_or_b32_e32 v6, 19, v8
	v_cmp_le_i32_e64 s[98:99], v6, v0
	s_nop 1
	v_cndmask_b32_e64 v225, 0, v225, s[98:99]
	v_or_b32_e32 v6, 20, v8
	v_cmp_le_i32_e64 s[98:99], v6, v0
	s_nop 1
	v_cndmask_b32_e64 v228, 0, v228, s[98:99]
	v_or_b32_e32 v6, 21, v8
	v_cmp_le_i32_e64 s[98:99], v6, v0
	s_nop 1
	v_cndmask_b32_e64 v227, 0, v227, s[98:99]
	v_or_b32_e32 v6, 22, v8
	v_cmp_le_i32_e64 s[98:99], v6, v0
	s_nop 1
	v_cndmask_b32_e64 v230, 0, v230, s[98:99]
	v_or_b32_e32 v6, 23, v8
	v_cmp_le_i32_e64 s[98:99], v6, v0
	s_nop 1
	v_cndmask_b32_e64 v229, 0, v229, s[98:99]

; #define MFMA32(a, b, c) __builtin_amdgcn_mfma_f32_32x32x16_bf16((a), (b), (c), 0, 0, 0)
; DI void a1_task(unsigned char* shm, const bf16_t* prm, const bf16_t* prt, unsigned* mask, int b, int qt, const int tid) {
;     ...
;             for (int hh = 0; hh < 8; ++hh) {
;                 bf16x8 qa[4];
; #pragma unroll
;                 for (int ks = 0; ks < 4; ++ks) qa[ks] = *(const bf16x8*)(qb0 + hh * 128 + 32 * ks);
;                 const float wv = wqs[hh * 32 + r];
;                 asm volatile("s_waitcnt lgkmcnt(0)" ::: "memory");
;                 f32x16 acc;
; #pragma unroll
;                 for (int i = 0; i < 16; ++i) acc[i] = 0.f;
; #pragma unroll
;                 for (int ks = 0; ks < 4; ++ks) acc = MFMA32(kf[ks], qa[ks], acc);
; #pragma unroll
;                 for (int i = 0; i < 16; ++i) idx[i] = fmaf(wv, fmaxf(acc[i], 0.f), idx[i]);
;             }
; #pragma unroll
;             for (int i = 0; i < 16; ++i) {
;                 const int s = s0 + 16 * (i >> 3) + 8 * h + (i & 7);
;                 const unsigned u = __float_as_uint(idx[i] + 0.0f);
;                 const unsigned k = (u & 0x80000000u) ? ~u : (u | 0x80000000u);
;                 key[jt][i] = (s <= t0 + r) ? k : 0u;
;             }
.LBB0_438:
	v_add_u32_e32 v199, s1, v118
	ds_read_b128 v[2:5], v199
	ds_read_b128 v[86:89], v199 offset:32
	ds_read_b128 v[94:97], v199 offset:64
	ds_read_b128 v[244:247], v199 offset:96
	v_add_u32_e32 v200, s1, v135
	s_waitcnt lgkmcnt(3)
	v_mfma_f32_32x32x16_bf16 v[2:17], v[50:53], v[2:5], 0
	ds_read_b32 v198, v200
	s_waitcnt lgkmcnt(0)
	s_addk_i32 s1, 0x100
	s_cmpk_lg_i32 s1, 0x400
	s_waitcnt lgkmcnt(3)
	v_mfma_f32_32x32x16_bf16 v[2:17], v[54:57], v[86:89], v[2:17]
	s_waitcnt lgkmcnt(2)
	v_mfma_f32_32x32x16_bf16 v[2:17], v[58:61], v[94:97], v[2:17]
	s_waitcnt lgkmcnt(1)
	v_mfma_f32_32x32x16_bf16 v[2:17], v[62:65], v[244:247], v[2:17]
	s_nop 11
	v_max_f32_e32 v2, 0, v2
	v_max_f32_e32 v3, 0, v3
	s_waitcnt lgkmcnt(0)
	v_pk_fma_f32 v[80:81], v[198:199], v[2:3], v[80:81] op_sel_hi:[0,1,1]
	v_max_f32_e32 v2, 0, v4
	v_max_f32_e32 v3, 0, v5
	v_pk_fma_f32 v[78:79], v[198:199], v[2:3], v[78:79] op_sel_hi:[0,1,1]
	v_max_f32_e32 v2, 0, v6
	v_max_f32_e32 v3, 0, v7
	v_pk_fma_f32 v[76:77], v[198:199], v[2:3], v[76:77] op_sel_hi:[0,1,1]
	v_max_f32_e32 v2, 0, v8
	v_max_f32_e32 v3, 0, v9
	v_pk_fma_f32 v[74:75], v[198:199], v[2:3], v[74:75] op_sel_hi:[0,1,1]
	v_max_f32_e32 v2, 0, v10
	v_max_f32_e32 v3, 0, v11
	v_pk_fma_f32 v[72:73], v[198:199], v[2:3], v[72:73] op_sel_hi:[0,1,1]
	v_max_f32_e32 v2, 0, v12
	v_max_f32_e32 v3, 0, v13
	v_pk_fma_f32 v[70:71], v[198:199], v[2:3], v[70:71] op_sel_hi:[0,1,1]
	v_max_f32_e32 v2, 0, v14
	v_max_f32_e32 v3, 0, v15
	v_pk_fma_f32 v[68:69], v[198:199], v[2:3], v[68:69] op_sel_hi:[0,1,1]
	v_max_f32_e32 v2, 0, v16
	v_max_f32_e32 v3, 0, v17
	v_pk_fma_f32 v[66:67], v[198:199], v[2:3], v[66:67] op_sel_hi:[0,1,1]
	ds_read_b128 v[2:5], v199 offset:128
	ds_read_b128 v[86:89], v199 offset:160
	ds_read_b128 v[94:97], v199 offset:192
	ds_read_b128 v[244:247], v199 offset:224
	ds_read_b32 v198, v200 offset:128
	s_waitcnt lgkmcnt(4)
	v_mfma_f32_32x32x16_bf16 v[2:17], v[50:53], v[2:5], 0
	s_waitcnt lgkmcnt(0)
	s_waitcnt lgkmcnt(3)
	v_mfma_f32_32x32x16_bf16 v[2:17], v[54:57], v[86:89], v[2:17]
	s_waitcnt lgkmcnt(2)
	v_mfma_f32_32x32x16_bf16 v[2:17], v[58:61], v[94:97], v[2:17]
	s_waitcnt lgkmcnt(1)
	v_mfma_f32_32x32x16_bf16 v[2:17], v[62:65], v[244:247], v[2:17]
	s_nop 11
	v_max_f32_e32 v2, 0, v2
	v_max_f32_e32 v3, 0, v3
	s_waitcnt lgkmcnt(0)
	v_pk_fma_f32 v[80:81], v[198:199], v[2:3], v[80:81] op_sel_hi:[0,1,1]
	v_max_f32_e32 v2, 0, v4
	v_max_f32_e32 v3, 0, v5
	v_pk_fma_f32 v[78:79], v[198:199], v[2:3], v[78:79] op_sel_hi:[0,1,1]
	v_max_f32_e32 v2, 0, v6
	v_max_f32_e32 v3, 0, v7
	v_pk_fma_f32 v[76:77], v[198:199], v[2:3], v[76:77] op_sel_hi:[0,1,1]
	v_max_f32_e32 v2, 0, v8
	v_max_f32_e32 v3, 0, v9
	v_pk_fma_f32 v[74:75], v[198:199], v[2:3], v[74:75] op_sel_hi:[0,1,1]
	v_max_f32_e32 v2, 0, v10
	v_max_f32_e32 v3, 0, v11
	v_pk_fma_f32 v[72:73], v[198:199], v[2:3], v[72:73] op_sel_hi:[0,1,1]
	v_max_f32_e32 v2, 0, v12
	v_max_f32_e32 v3, 0, v13
	v_pk_fma_f32 v[70:71], v[198:199], v[2:3], v[70:71] op_sel_hi:[0,1,1]
	v_max_f32_e32 v2, 0, v14
	v_max_f32_e32 v3, 0, v15
	v_pk_fma_f32 v[68:69], v[198:199], v[2:3], v[68:69] op_sel_hi:[0,1,1]
	v_max_f32_e32 v2, 0, v16
	v_max_f32_e32 v3, 0, v17
	v_pk_fma_f32 v[66:67], v[198:199], v[2:3], v[66:67] op_sel_hi:[0,1,1]
	s_cbranch_scc1 .LBB0_438
	v_pk_add_f32 v[2:3], v[80:81], 0 op_sel_hi:[1,0]
	v_ashrrev_i32_e32 v4, 31, v2
	v_ashrrev_i32_e32 v5, 31, v3
	v_or_b32_e32 v4, 0x80000000, v4
	v_or_b32_e32 v5, 0x80000000, v5
	v_xor_b32_e32 v87, v2, v4
	v_xor_b32_e32 v86, v3, v5
	v_pk_add_f32 v[2:3], v[78:79], 0 op_sel_hi:[1,0]
	v_ashrrev_i32_e32 v4, 31, v2
	v_ashrrev_i32_e32 v5, 31, v3
	v_or_b32_e32 v4, 0x80000000, v4
	v_or_b32_e32 v5, 0x80000000, v5
	v_xor_b32_e32 v89, v2, v4
	v_xor_b32_e32 v88, v3, v5
	v_pk_add_f32 v[2:3], v[76:77], 0 op_sel_hi:[1,0]
	v_ashrrev_i32_e32 v4, 31, v2
	v_ashrrev_i32_e32 v5, 31, v3
	v_or_b32_e32 v4, 0x80000000, v4
	v_or_b32_e32 v5, 0x80000000, v5
	v_xor_b32_e32 v95, v2, v4
	v_xor_b32_e32 v94, v3, v5
	v_pk_add_f32 v[2:3], v[74:75], 0 op_sel_hi:[1,0]
	v_ashrrev_i32_e32 v4, 31, v2
	v_ashrrev_i32_e32 v5, 31, v3
	v_or_b32_e32 v4, 0x80000000, v4
	v_or_b32_e32 v5, 0x80000000, v5
	v_xor_b32_e32 v97, v2, v4
	v_xor_b32_e32 v96, v3, v5
	v_pk_add_f32 v[2:3], v[72:73], 0 op_sel_hi:[1,0]
	v_ashrrev_i32_e32 v4, 31, v2
	v_ashrrev_i32_e32 v5, 31, v3
	v_or_b32_e32 v4, 0x80000000, v4
	v_or_b32_e32 v5, 0x80000000, v5
	v_xor_b32_e32 v244, v2, v4
	v_xor_b32_e32 v231, v3, v5
	v_pk_add_f32 v[2:3], v[70:71], 0 op_sel_hi:[1,0]
	v_ashrrev_i32_e32 v4, 31, v2
	v_ashrrev_i32_e32 v5, 31, v3
	v_or_b32_e32 v4, 0x80000000, v4
	v_or_b32_e32 v5, 0x80000000, v5
	v_xor_b32_e32 v246, v2, v4
	v_xor_b32_e32 v245, v3, v5
	v_pk_add_f32 v[2:3], v[68:69], 0 op_sel_hi:[1,0]
	v_ashrrev_i32_e32 v4, 31, v2
	v_ashrrev_i32_e32 v5, 31, v3
	v_or_b32_e32 v4, 0x80000000, v4
	v_or_b32_e32 v5, 0x80000000, v5
	v_xor_b32_e32 v248, v2, v4
	v_xor_b32_e32 v247, v3, v5
	v_pk_add_f32 v[2:3], v[66:67], 0 op_sel_hi:[1,0]
	v_ashrrev_i32_e32 v4, 31, v2
	v_ashrrev_i32_e32 v5, 31, v3
	v_or_b32_e32 v4, 0x80000000, v4
	v_or_b32_e32 v5, 0x80000000, v5
	v_xor_b32_e32 v250, v2, v4
	v_xor_b32_e32 v249, v3, v5
	s_lshr_b32 s98, s0, 5
	s_cmp_lt_u32 s98, s2
	s_cbranch_scc1 .Lkc_done_438
	v_or_b32_e32 v8, s0, v98
	v_cmp_le_i32_e64 s[98:99], v8, v0
	s_nop 1
	v_cndmask_b32_e64 v87, 0, v87, s[98:99]
	v_or_b32_e32 v6, 1, v8
	v_cmp_le_i32_e64 s[98:99], v6, v0
	s_nop 1
	v_cndmask_b32_e64 v86, 0, v86, s[98:99]
	v_or_b32_e32 v6, 2, v8
	v_cmp_le_i32_e64 s[98:99], v6, v0
	s_nop 1
	v_cndmask_b32_e64 v89, 0, v89, s[98:99]
	v_or_b32_e32 v6, 3, v8
	v_cmp_le_i32_e64 s[98:99], v6, v0
	s_nop 1
	v_cndmask_b32_e64 v88, 0, v88, s[98:99]
	v_or_b32_e32 v6, 4, v8
	v_cmp_le_i32_e64 s[98:99], v6, v0
	s_nop 1
	v_cndmask_b32_e64 v95, 0, v95, s[98:99]
	v_or_b32_e32 v6, 5, v8
	v_cmp_le_i32_e64 s[98:99], v6, v0
	s_nop 1
	v_cndmask_b32_e64 v94, 0, v94, s[98:99]
	v_or_b32_e32 v6, 6, v8
	v_cmp_le_i32_e64 s[98:99], v6, v0
	s_nop 1
	v_cndmask_b32_e64 v97, 0, v97, s[98:99]
	v_or_b32_e32 v6, 7, v8
	v_cmp_le_i32_e64 s[98:99], v6, v0
	s_nop 1
	v_cndmask_b32_e64 v96, 0, v96, s[98:99]
	v_or_b32_e32 v6, 16, v8
	v_cmp_le_i32_e64 s[98:99], v6, v0
	s_nop 1
	v_cndmask_b32_e64 v244, 0, v244, s[98:99]
	v_or_b32_e32 v6, 17, v8
	v_cmp_le_i32_e64 s[98:99], v6, v0
	s_nop 1
	v_cndmask_b32_e64 v231, 0, v231, s[98:99]
	v_or_b32_e32 v6, 18, v8
	v_cmp_le_i32_e64 s[98:99], v6, v0
	s_nop 1
	v_cndmask_b32_e64 v246, 0, v246, s[98:99]
	v_or_b32_e32 v6, 19, v8
	v_cmp_le_i32_e64 s[98:99], v6, v0
	s_nop 1
	v_cndmask_b32_e64 v245, 0, v245, s[98:99]
	v_or_b32_e32 v6, 20, v8
	v_cmp_le_i32_e64 s[98:99], v6, v0
	s_nop 1
	v_cndmask_b32_e64 v248, 0, v248, s[98:99]
	v_or_b32_e32 v6, 21, v8
	v_cmp_le_i32_e64 s[98:99], v6, v0
	s_nop 1
	v_cndmask_b32_e64 v247, 0, v247, s[98:99]
	v_or_b32_e32 v6, 22, v8
	v_cmp_le_i32_e64 s[98:99], v6, v0
	s_nop 1
	v_cndmask_b32_e64 v250, 0, v250, s[98:99]
	v_or_b32_e32 v6, 23, v8
	v_cmp_le_i32_e64 s[98:99], v6, v0
	s_nop 1
	v_cndmask_b32_e64 v249, 0, v249, s[98:99]

; #define MFMA32(a, b, c) __builtin_amdgcn_mfma_f32_32x32x16_bf16((a), (b), (c), 0, 0, 0)
; DI void a1_task(unsigned char* shm, const bf16_t* prm, const bf16_t* prt, unsigned* mask, int b, int qt, const int tid) {
;     ...
;             for (int hh = 0; hh < 8; ++hh) {
;                 bf16x8 qa[4];
; #pragma unroll
;                 for (int ks = 0; ks < 4; ++ks) qa[ks] = *(const bf16x8*)(qb0 + hh * 128 + 32 * ks);
;                 const float wv = wqs[hh * 32 + r];
;                 asm volatile("s_waitcnt lgkmcnt(0)" ::: "memory");
;                 f32x16 acc;
; #pragma unroll
;                 for (int i = 0; i < 16; ++i) acc[i] = 0.f;
; #pragma unroll
;                 for (int ks = 0; ks < 4; ++ks) acc = MFMA32(kf[ks], qa[ks], acc);
; #pragma unroll
;                 for (int i = 0; i < 16; ++i) idx[i] = fmaf(wv, fmaxf(acc[i], 0.f), idx[i]);
;             }
; #pragma unroll
;             for (int i = 0; i < 16; ++i) {
;                 const int s = s0 + 16 * (i >> 3) + 8 * h + (i & 7);
;                 const unsigned u = __float_as_uint(idx[i] + 0.0f);
;                 const unsigned k = (u & 0x80000000u) ? ~u : (u | 0x80000000u);
;                 key[jt][i] = (s <= t0 + r) ? k : 0u;
;             }
.LBB0_448:
	v_add_u32_e32 v63, s1, v118
	ds_read_b128 v[2:5], v63
	ds_read_b128 v[50:53], v63 offset:32
	ds_read_b128 v[54:57], v63 offset:64
	ds_read_b128 v[58:61], v63 offset:96
	v_add_u32_e32 v64, s1, v135
	s_waitcnt lgkmcnt(3)
	v_mfma_f32_32x32x16_bf16 v[2:17], v[66:69], v[2:5], 0
	ds_read_b32 v62, v64
	s_waitcnt lgkmcnt(0)
	s_addk_i32 s1, 0x100
	s_cmpk_lg_i32 s1, 0x400
	s_waitcnt lgkmcnt(3)
	v_mfma_f32_32x32x16_bf16 v[2:17], v[70:73], v[50:53], v[2:17]
	s_waitcnt lgkmcnt(2)
	v_mfma_f32_32x32x16_bf16 v[2:17], v[74:77], v[54:57], v[2:17]
	s_waitcnt lgkmcnt(1)
	v_mfma_f32_32x32x16_bf16 v[2:17], v[78:81], v[58:61], v[2:17]
	s_nop 11
	v_max_f32_e32 v2, 0, v2
	v_max_f32_e32 v3, 0, v3
	s_waitcnt lgkmcnt(0)
	v_pk_fma_f32 v[32:33], v[62:63], v[2:3], v[32:33] op_sel_hi:[0,1,1]
	v_max_f32_e32 v2, 0, v4
	v_max_f32_e32 v3, 0, v5
	v_pk_fma_f32 v[30:31], v[62:63], v[2:3], v[30:31] op_sel_hi:[0,1,1]
	v_max_f32_e32 v2, 0, v6
	v_max_f32_e32 v3, 0, v7
	v_pk_fma_f32 v[28:29], v[62:63], v[2:3], v[28:29] op_sel_hi:[0,1,1]
	v_max_f32_e32 v2, 0, v8
	v_max_f32_e32 v3, 0, v9
	v_pk_fma_f32 v[26:27], v[62:63], v[2:3], v[26:27] op_sel_hi:[0,1,1]
	v_max_f32_e32 v2, 0, v10
	v_max_f32_e32 v3, 0, v11
	v_pk_fma_f32 v[24:25], v[62:63], v[2:3], v[24:25] op_sel_hi:[0,1,1]
	v_max_f32_e32 v2, 0, v12
	v_max_f32_e32 v3, 0, v13
	v_pk_fma_f32 v[22:23], v[62:63], v[2:3], v[22:23] op_sel_hi:[0,1,1]
	v_max_f32_e32 v2, 0, v14
	v_max_f32_e32 v3, 0, v15
	v_pk_fma_f32 v[20:21], v[62:63], v[2:3], v[20:21] op_sel_hi:[0,1,1]
	v_max_f32_e32 v2, 0, v16
	v_max_f32_e32 v3, 0, v17
	v_pk_fma_f32 v[18:19], v[62:63], v[2:3], v[18:19] op_sel_hi:[0,1,1]
	ds_read_b128 v[2:5], v63 offset:128
	ds_read_b128 v[50:53], v63 offset:160
	ds_read_b128 v[54:57], v63 offset:192
	ds_read_b128 v[58:61], v63 offset:224
	ds_read_b32 v62, v64 offset:128
	s_waitcnt lgkmcnt(4)
	v_mfma_f32_32x32x16_bf16 v[2:17], v[66:69], v[2:5], 0
	s_waitcnt lgkmcnt(0)
	s_waitcnt lgkmcnt(3)
	v_mfma_f32_32x32x16_bf16 v[2:17], v[70:73], v[50:53], v[2:17]
	s_waitcnt lgkmcnt(2)
	v_mfma_f32_32x32x16_bf16 v[2:17], v[74:77], v[54:57], v[2:17]
	s_waitcnt lgkmcnt(1)
	v_mfma_f32_32x32x16_bf16 v[2:17], v[78:81], v[58:61], v[2:17]
	s_nop 11
	v_max_f32_e32 v2, 0, v2
	v_max_f32_e32 v3, 0, v3
	s_waitcnt lgkmcnt(0)
	v_pk_fma_f32 v[32:33], v[62:63], v[2:3], v[32:33] op_sel_hi:[0,1,1]
	v_max_f32_e32 v2, 0, v4
	v_max_f32_e32 v3, 0, v5
	v_pk_fma_f32 v[30:31], v[62:63], v[2:3], v[30:31] op_sel_hi:[0,1,1]
	v_max_f32_e32 v2, 0, v6
	v_max_f32_e32 v3, 0, v7
	v_pk_fma_f32 v[28:29], v[62:63], v[2:3], v[28:29] op_sel_hi:[0,1,1]
	v_max_f32_e32 v2, 0, v8
	v_max_f32_e32 v3, 0, v9
	v_pk_fma_f32 v[26:27], v[62:63], v[2:3], v[26:27] op_sel_hi:[0,1,1]
	v_max_f32_e32 v2, 0, v10
	v_max_f32_e32 v3, 0, v11
	v_pk_fma_f32 v[24:25], v[62:63], v[2:3], v[24:25] op_sel_hi:[0,1,1]
	v_max_f32_e32 v2, 0, v12
	v_max_f32_e32 v3, 0, v13
	v_pk_fma_f32 v[22:23], v[62:63], v[2:3], v[22:23] op_sel_hi:[0,1,1]
	v_max_f32_e32 v2, 0, v14
	v_max_f32_e32 v3, 0, v15
	v_pk_fma_f32 v[20:21], v[62:63], v[2:3], v[20:21] op_sel_hi:[0,1,1]
	v_max_f32_e32 v2, 0, v16
	v_max_f32_e32 v3, 0, v17
	v_pk_fma_f32 v[18:19], v[62:63], v[2:3], v[18:19] op_sel_hi:[0,1,1]
	s_cbranch_scc1 .LBB0_448
	v_pk_add_f32 v[2:3], v[32:33], 0 op_sel_hi:[1,0]
	v_ashrrev_i32_e32 v4, 31, v2
	v_ashrrev_i32_e32 v5, 31, v3
	v_or_b32_e32 v4, 0x80000000, v4
	v_or_b32_e32 v5, 0x80000000, v5
	v_xor_b32_e32 v51, v2, v4
	v_xor_b32_e32 v50, v3, v5
	v_pk_add_f32 v[2:3], v[30:31], 0 op_sel_hi:[1,0]
	v_ashrrev_i32_e32 v4, 31, v2
	v_ashrrev_i32_e32 v5, 31, v3
	v_or_b32_e32 v4, 0x80000000, v4
	v_or_b32_e32 v5, 0x80000000, v5
	v_xor_b32_e32 v53, v2, v4
	v_xor_b32_e32 v52, v3, v5
	v_pk_add_f32 v[2:3], v[28:29], 0 op_sel_hi:[1,0]
	v_ashrrev_i32_e32 v4, 31, v2
	v_ashrrev_i32_e32 v5, 31, v3
	v_or_b32_e32 v4, 0x80000000, v4
	v_or_b32_e32 v5, 0x80000000, v5
	v_xor_b32_e32 v55, v2, v4
	v_xor_b32_e32 v54, v3, v5
	v_pk_add_f32 v[2:3], v[26:27], 0 op_sel_hi:[1,0]
	v_ashrrev_i32_e32 v4, 31, v2
	v_ashrrev_i32_e32 v5, 31, v3
	v_or_b32_e32 v4, 0x80000000, v4
	v_or_b32_e32 v5, 0x80000000, v5
	v_xor_b32_e32 v57, v2, v4
	v_xor_b32_e32 v56, v3, v5
	v_pk_add_f32 v[2:3], v[24:25], 0 op_sel_hi:[1,0]
	v_ashrrev_i32_e32 v4, 31, v2
	v_ashrrev_i32_e32 v5, 31, v3
	v_or_b32_e32 v4, 0x80000000, v4
	v_or_b32_e32 v5, 0x80000000, v5
	v_xor_b32_e32 v59, v2, v4
	v_xor_b32_e32 v58, v3, v5
	v_pk_add_f32 v[2:3], v[22:23], 0 op_sel_hi:[1,0]
	v_ashrrev_i32_e32 v4, 31, v2
	v_ashrrev_i32_e32 v5, 31, v3
	v_or_b32_e32 v4, 0x80000000, v4
	v_or_b32_e32 v5, 0x80000000, v5
	v_xor_b32_e32 v61, v2, v4
	v_xor_b32_e32 v60, v3, v5
	v_pk_add_f32 v[2:3], v[20:21], 0 op_sel_hi:[1,0]
	v_ashrrev_i32_e32 v4, 31, v2
	v_ashrrev_i32_e32 v5, 31, v3
	v_or_b32_e32 v4, 0x80000000, v4
	v_or_b32_e32 v5, 0x80000000, v5
	v_xor_b32_e32 v63, v2, v4
	v_xor_b32_e32 v62, v3, v5
	v_pk_add_f32 v[2:3], v[18:19], 0 op_sel_hi:[1,0]
	v_ashrrev_i32_e32 v4, 31, v2
	v_ashrrev_i32_e32 v5, 31, v3
	v_or_b32_e32 v4, 0x80000000, v4
	v_or_b32_e32 v5, 0x80000000, v5
	v_xor_b32_e32 v65, v2, v4
	v_xor_b32_e32 v64, v3, v5
	s_lshr_b32 s98, s0, 5
	s_cmp_lt_u32 s98, s2
	s_cbranch_scc1 .Lkc_done_448
	v_or_b32_e32 v8, s0, v98
	v_cmp_le_i32_e64 s[98:99], v8, v0
	s_nop 1
	v_cndmask_b32_e64 v51, 0, v51, s[98:99]
	v_or_b32_e32 v6, 1, v8
	v_cmp_le_i32_e64 s[98:99], v6, v0
	s_nop 1
	v_cndmask_b32_e64 v50, 0, v50, s[98:99]
	v_or_b32_e32 v6, 2, v8
	v_cmp_le_i32_e64 s[98:99], v6, v0
	s_nop 1
	v_cndmask_b32_e64 v53, 0, v53, s[98:99]
	v_or_b32_e32 v6, 3, v8
	v_cmp_le_i32_e64 s[98:99], v6, v0
	s_nop 1
	v_cndmask_b32_e64 v52, 0, v52, s[98:99]
	v_or_b32_e32 v6, 4, v8
	v_cmp_le_i32_e64 s[98:99], v6, v0
	s_nop 1
	v_cndmask_b32_e64 v55, 0, v55, s[98:99]
	v_or_b32_e32 v6, 5, v8
	v_cmp_le_i32_e64 s[98:99], v6, v0
	s_nop 1
	v_cndmask_b32_e64 v54, 0, v54, s[98:99]
	v_or_b32_e32 v6, 6, v8
	v_cmp_le_i32_e64 s[98:99], v6, v0
	s_nop 1
	v_cndmask_b32_e64 v57, 0, v57, s[98:99]
	v_or_b32_e32 v6, 7, v8
	v_cmp_le_i32_e64 s[98:99], v6, v0
	s_nop 1
	v_cndmask_b32_e64 v56, 0, v56, s[98:99]
	v_or_b32_e32 v6, 16, v8
	v_cmp_le_i32_e64 s[98:99], v6, v0
	s_nop 1
	v_cndmask_b32_e64 v59, 0, v59, s[98:99]
	v_or_b32_e32 v6, 17, v8
	v_cmp_le_i32_e64 s[98:99], v6, v0
	s_nop 1
	v_cndmask_b32_e64 v58, 0, v58, s[98:99]
	v_or_b32_e32 v6, 18, v8
	v_cmp_le_i32_e64 s[98:99], v6, v0
	s_nop 1
	v_cndmask_b32_e64 v61, 0, v61, s[98:99]
	v_or_b32_e32 v6, 19, v8
	v_cmp_le_i32_e64 s[98:99], v6, v0
	s_nop 1
	v_cndmask_b32_e64 v60, 0, v60, s[98:99]
	v_or_b32_e32 v6, 20, v8
	v_cmp_le_i32_e64 s[98:99], v6, v0
	s_nop 1
	v_cndmask_b32_e64 v63, 0, v63, s[98:99]
	v_or_b32_e32 v6, 21, v8
	v_cmp_le_i32_e64 s[98:99], v6, v0
	s_nop 1
	v_cndmask_b32_e64 v62, 0, v62, s[98:99]
	v_or_b32_e32 v6, 22, v8
	v_cmp_le_i32_e64 s[98:99], v6, v0
	s_nop 1
	v_cndmask_b32_e64 v65, 0, v65, s[98:99]
	v_or_b32_e32 v6, 23, v8
	v_cmp_le_i32_e64 s[98:99], v6, v0
	s_nop 1
	v_cndmask_b32_e64 v64, 0, v64, s[98:99]
